# P8a prompt path: dropped the per-fetch vmcnt(0) in front of each window-row load for the W=8 and W=16 column groups (loads of one item now pipelined)
# speedup vs baseline: 1.0179x; 1.0096x over previous
.LBB0_1744:
	s_andn2_b64 vcc, exec, s[28:29]
	s_cbranch_vccnz .LBB0_1747
	v_mov_b32_e32 v3, 0
	s_and_b64 vcc, exec, s[0:1]
	v_mov_b32_e32 v2, 0
	v_mov_b32_e32 v1, 0
	v_mov_b32_e32 v0, 0
	s_cbranch_vccnz .LBB0_1747
	s_and_b32 s0, s18, 0xfffff000
	s_add_i32 s0, s0, s19
	s_ashr_i32 s1, s0, 31
	s_lshl_b64 s[0:1], s[0:1], 13
	v_lshl_add_u64 v[0:1], v[94:95], 0, s[0:1]
	global_load_dwordx4 v[0:3], v[0:1], off

.LBB0_1764:
	s_and_b64 vcc, exec, s[10:11]
	s_cbranch_vccnz .LBB0_1772
	s_and_b32 s52, s18, 0xfffff000
	s_add_i32 s52, s52, s19
	s_ashr_i32 s53, s52, 31
	s_lshl_b64 s[52:53], s[52:53], 13
	v_lshl_add_u64 v[12:13], v[86:87], 0, s[52:53]
	global_load_dwordx4 v[12:15], v[12:13], off

.LBB0_1772:
	v_mov_b32_e32 v15, 0
	v_mov_b32_e32 v14, v15
	v_mov_b32_e32 v13, v15
	v_mov_b32_e32 v12, v15
	s_add_i32 s19, s20, -3
	s_and_b64 vcc, exec, s[8:9]
	s_mov_b64 s[52:53], -1
	s_cbranch_vccz .LBB0_1767

.LBB0_1774:
	s_and_b64 vcc, exec, s[10:11]
	s_cbranch_vccnz .LBB0_1782
	s_and_b32 s52, s18, 0xfffff000
	s_add_i32 s52, s52, s19
	s_ashr_i32 s53, s52, 31
	s_lshl_b64 s[52:53], s[52:53], 13
	v_lshl_add_u64 v[16:17], v[86:87], 0, s[52:53]
	global_load_dwordx4 v[16:19], v[16:17], off

.LBB0_1782:
	v_mov_b32_e32 v19, 0
	v_mov_b32_e32 v18, v19
	v_mov_b32_e32 v17, v19
	v_mov_b32_e32 v16, v19
	s_add_i32 s19, s20, -2
	s_and_b64 vcc, exec, s[8:9]
	s_mov_b64 s[52:53], -1
	s_cbranch_vccz .LBB0_1777

.LBB0_1784:
	s_and_b64 vcc, exec, s[10:11]
	s_cbranch_vccnz .LBB0_1971
	s_and_b32 s52, s18, 0xfffff000
	s_add_i32 s52, s52, s19
	s_ashr_i32 s53, s52, 31
	s_lshl_b64 s[52:53], s[52:53], 13
	v_lshl_add_u64 v[20:21], v[86:87], 0, s[52:53]
	global_load_dwordx4 v[20:23], v[20:21], off

.LBB0_1791:
	s_andn2_b64 vcc, exec, s[52:53]
	v_readlane_b32 s52, v254, 54
	s_mov_b32 s92, s52
	v_readlane_b32 s53, v254, 55
	s_cbranch_vccnz .LBB0_1798
	s_and_b64 vcc, exec, s[10:11]
	s_cbranch_vccnz .LBB0_1973
	s_and_b32 s10, s18, 0xfffff000
	s_add_i32 s10, s10, s19
	s_ashr_i32 s11, s10, 31
	s_lshl_b64 s[10:11], s[10:11], 13
	v_lshl_add_u64 v[24:25], v[86:87], 0, s[10:11]
	global_load_dwordx4 v[24:27], v[24:25], off
	s_and_b64 vcc, exec, s[8:9]
	s_mov_b64 s[10:11], -1
	s_cbranch_vccz .LBB0_1799

.LBB0_1819:
	s_andn2_b64 vcc, exec, s[10:11]
	s_cbranch_vccnz .LBB0_1822
	v_mov_b32_e32 v3, 0
	s_andn2_b64 vcc, exec, s[8:9]
	v_mov_b32_e32 v2, 0
	v_mov_b32_e32 v1, 0
	v_mov_b32_e32 v0, 0
	s_cbranch_vccnz .LBB0_1822
	s_and_b32 s8, s18, 0xfffff000
	s_add_i32 s8, s8, s19
	s_ashr_i32 s9, s8, 31
	s_lshl_b64 s[8:9], s[8:9], 13
	v_lshl_add_u64 v[0:1], v[86:87], 0, s[8:9]
	global_load_dwordx4 v[0:3], v[0:1], off

.LBB0_1828:
	s_andn2_b64 vcc, exec, s[40:41]
	s_cbranch_vccnz .LBB0_1831
	v_mov_b32_e32 v7, 0
	s_andn2_b64 vcc, exec, s[10:11]
	v_mov_b32_e32 v6, 0
	v_mov_b32_e32 v5, 0
	v_mov_b32_e32 v4, 0
	s_cbranch_vccnz .LBB0_1831
	s_and_b32 s10, s18, 0xfffff000
	s_add_i32 s10, s10, s19
	s_ashr_i32 s11, s10, 31
	s_lshl_b64 s[10:11], s[10:11], 13
	v_lshl_add_u64 v[4:5], v[86:87], 0, s[10:11]
	global_load_dwordx4 v[4:7], v[4:5], off

.LBB0_1837:
	s_andn2_b64 vcc, exec, s[40:41]
	s_cbranch_vccnz .LBB0_1840
	v_mov_b32_e32 v11, 0
	s_andn2_b64 vcc, exec, s[10:11]
	v_mov_b32_e32 v10, 0
	v_mov_b32_e32 v9, 0
	v_mov_b32_e32 v8, 0
	s_cbranch_vccnz .LBB0_1840
	s_and_b32 s10, s18, 0xfffff000
	s_add_i32 s10, s10, s19
	s_ashr_i32 s11, s10, 31
	s_lshl_b64 s[10:11], s[10:11], 13
	v_lshl_add_u64 v[8:9], v[86:87], 0, s[10:11]
	global_load_dwordx4 v[8:11], v[8:9], off

.LBB0_1846:
	s_andn2_b64 vcc, exec, s[40:41]
	s_cbranch_vccnz .LBB0_1849
	v_mov_b32_e32 v15, 0
	s_andn2_b64 vcc, exec, s[10:11]
	v_mov_b32_e32 v14, 0
	v_mov_b32_e32 v13, 0
	v_mov_b32_e32 v12, 0
	s_cbranch_vccnz .LBB0_1849
	s_and_b32 s10, s18, 0xfffff000
	s_add_i32 s10, s10, s19
	s_ashr_i32 s11, s10, 31
	s_lshl_b64 s[10:11], s[10:11], 13
	v_lshl_add_u64 v[12:13], v[86:87], 0, s[10:11]
	global_load_dwordx4 v[12:15], v[12:13], off

.LBB0_1855:
	s_andn2_b64 vcc, exec, s[40:41]
	s_cbranch_vccnz .LBB0_1858
	v_mov_b32_e32 v19, 0
	s_andn2_b64 vcc, exec, s[10:11]
	v_mov_b32_e32 v18, 0
	v_mov_b32_e32 v17, 0
	v_mov_b32_e32 v16, 0
	s_cbranch_vccnz .LBB0_1858
	s_and_b32 s10, s18, 0xfffff000
	s_add_i32 s10, s10, s19
	s_ashr_i32 s11, s10, 31
	s_lshl_b64 s[10:11], s[10:11], 13
	v_lshl_add_u64 v[16:17], v[86:87], 0, s[10:11]
	global_load_dwordx4 v[16:19], v[16:17], off

.LBB0_1864:
	s_andn2_b64 vcc, exec, s[40:41]
	s_cbranch_vccnz .LBB0_1867
	v_mov_b32_e32 v23, 0
	s_andn2_b64 vcc, exec, s[10:11]
	v_mov_b32_e32 v22, 0
	v_mov_b32_e32 v21, 0
	v_mov_b32_e32 v20, 0
	s_cbranch_vccnz .LBB0_1867
	s_and_b32 s10, s18, 0xfffff000
	s_add_i32 s10, s10, s19
	s_ashr_i32 s11, s10, 31
	s_lshl_b64 s[10:11], s[10:11], 13
	v_lshl_add_u64 v[20:21], v[86:87], 0, s[10:11]
	global_load_dwordx4 v[20:23], v[20:21], off

.LBB0_1873:
	s_andn2_b64 vcc, exec, s[40:41]
	s_cbranch_vccnz .LBB0_1876
	v_mov_b32_e32 v27, 0
	s_andn2_b64 vcc, exec, s[10:11]
	v_mov_b32_e32 v26, 0
	v_mov_b32_e32 v25, 0
	v_mov_b32_e32 v24, 0
	s_cbranch_vccnz .LBB0_1876
	s_and_b32 s10, s18, 0xfffff000
	s_add_i32 s10, s10, s19
	s_ashr_i32 s11, s10, 31
	s_lshl_b64 s[10:11], s[10:11], 13
	v_lshl_add_u64 v[24:25], v[86:87], 0, s[10:11]
	global_load_dwordx4 v[24:27], v[24:25], off

.LBB0_1882:
	s_andn2_b64 vcc, exec, s[40:41]
	s_cbranch_vccnz .LBB0_1885
	v_mov_b32_e32 v31, 0
	s_andn2_b64 vcc, exec, s[10:11]
	v_mov_b32_e32 v30, 0
	v_mov_b32_e32 v29, 0
	v_mov_b32_e32 v28, 0
	s_cbranch_vccnz .LBB0_1885
	s_and_b32 s10, s18, 0xfffff000
	s_add_i32 s10, s10, s19
	s_ashr_i32 s11, s10, 31
	s_lshl_b64 s[10:11], s[10:11], 13
	v_lshl_add_u64 v[28:29], v[86:87], 0, s[10:11]
	global_load_dwordx4 v[28:31], v[28:29], off

.LBB0_1891:
	s_andn2_b64 vcc, exec, s[40:41]
	s_cbranch_vccnz .LBB0_1894
	v_mov_b32_e32 v35, 0
	s_andn2_b64 vcc, exec, s[10:11]
	v_mov_b32_e32 v34, 0
	v_mov_b32_e32 v33, 0
	v_mov_b32_e32 v32, 0
	s_cbranch_vccnz .LBB0_1894
	s_and_b32 s10, s18, 0xfffff000
	s_add_i32 s10, s10, s19
	s_ashr_i32 s11, s10, 31
	s_lshl_b64 s[10:11], s[10:11], 13
	v_lshl_add_u64 v[32:33], v[86:87], 0, s[10:11]
	global_load_dwordx4 v[32:35], v[32:33], off

.LBB0_1900:
	s_andn2_b64 vcc, exec, s[40:41]
	s_cbranch_vccnz .LBB0_1903
	v_mov_b32_e32 v39, 0
	s_andn2_b64 vcc, exec, s[10:11]
	v_mov_b32_e32 v38, 0
	v_mov_b32_e32 v37, 0
	v_mov_b32_e32 v36, 0
	s_cbranch_vccnz .LBB0_1903
	s_and_b32 s10, s18, 0xfffff000
	s_add_i32 s10, s10, s19
	s_ashr_i32 s11, s10, 31
	s_lshl_b64 s[10:11], s[10:11], 13
	v_lshl_add_u64 v[36:37], v[86:87], 0, s[10:11]
	global_load_dwordx4 v[36:39], v[36:37], off

.LBB0_1909:
	s_andn2_b64 vcc, exec, s[40:41]
	s_cbranch_vccnz .LBB0_1912
	v_mov_b32_e32 v43, 0
	s_andn2_b64 vcc, exec, s[10:11]
	v_mov_b32_e32 v42, 0
	v_mov_b32_e32 v41, 0
	v_mov_b32_e32 v40, 0
	s_cbranch_vccnz .LBB0_1912
	s_and_b32 s10, s18, 0xfffff000
	s_add_i32 s10, s10, s19
	s_ashr_i32 s11, s10, 31
	s_lshl_b64 s[10:11], s[10:11], 13
	v_lshl_add_u64 v[40:41], v[86:87], 0, s[10:11]
	global_load_dwordx4 v[40:43], v[40:41], off

.LBB0_1918:
	s_and_b64 vcc, exec, s[10:11]
	s_cbranch_vccnz .LBB0_1926
	s_and_b32 s44, s18, 0xfffff000
	s_add_i32 s44, s44, s19
	s_ashr_i32 s45, s44, 31
	s_lshl_b64 s[44:45], s[44:45], 13
	v_lshl_add_u64 v[44:45], v[86:87], 0, s[44:45]
	global_load_dwordx4 v[44:47], v[44:45], off

.LBB0_1926:
	v_mov_b32_e32 v47, 0
	v_mov_b32_e32 v46, v47
	v_mov_b32_e32 v45, v47
	v_mov_b32_e32 v44, v47
	s_add_i32 s19, s20, -3
	s_and_b64 vcc, exec, s[8:9]
	s_mov_b64 s[44:45], -1
	s_cbranch_vccz .LBB0_1921

.LBB0_1928:
	s_and_b64 vcc, exec, s[10:11]
	s_cbranch_vccnz .LBB0_1936
	s_and_b32 s44, s18, 0xfffff000
	s_add_i32 s44, s44, s19
	s_ashr_i32 s45, s44, 31
	s_lshl_b64 s[44:45], s[44:45], 13
	v_lshl_add_u64 v[48:49], v[86:87], 0, s[44:45]
	global_load_dwordx4 v[48:51], v[48:49], off

.LBB0_1936:
	v_mov_b32_e32 v51, 0
	v_mov_b32_e32 v50, v51
	v_mov_b32_e32 v49, v51
	v_mov_b32_e32 v48, v51
	s_add_i32 s19, s20, -2
	s_and_b64 vcc, exec, s[8:9]
	s_mov_b64 s[44:45], -1
	s_cbranch_vccz .LBB0_1931

.LBB0_1938:
	s_and_b64 vcc, exec, s[10:11]
	s_cbranch_vccnz .LBB0_1948
	s_and_b32 s44, s18, 0xfffff000
	s_add_i32 s44, s44, s19
	s_ashr_i32 s45, s44, 31
	s_lshl_b64 s[44:45], s[44:45], 13
	v_lshl_add_u64 v[52:53], v[86:87], 0, s[44:45]
	global_load_dwordx4 v[52:55], v[52:53], off

.LBB0_1948:
	v_mov_b32_e32 v55, 0
	v_mov_b32_e32 v54, v55
	v_mov_b32_e32 v53, v55
	v_mov_b32_e32 v52, v55
	s_add_i32 s19, s20, -1
	s_and_b64 vcc, exec, s[8:9]
	s_mov_b64 s[44:45], -1
	s_cbranch_vccz .LBB0_1941

.LBB0_1950:
	s_and_b64 vcc, exec, s[10:11]
	s_cbranch_vccnz .LBB0_1969
	s_and_b32 s10, s18, 0xfffff000
	s_add_i32 s10, s10, s19
	s_ashr_i32 s11, s10, 31
	s_lshl_b64 s[10:11], s[10:11], 13
	v_lshl_add_u64 v[56:57], v[86:87], 0, s[10:11]
	global_load_dwordx4 v[56:59], v[56:57], off
	s_and_b64 vcc, exec, s[8:9]
	s_mov_b64 s[10:11], -1
	s_cbranch_vccz .LBB0_1946
